# GEMM prologues: K-tile-1 LDS-DMA loads issued with K-tile-0 loads, first wait vmcnt(8); plus epiconv, spatial LDS, sc1
# baseline (speedup 1.0000x reference)
.LBB0_346:
	s_add_u32 s60, s74, 0x4000000
	s_addc_u32 s61, s75, 0
	s_add_u32 s62, s74, 0x4600000
	s_addc_u32 s63, s75, 0
	s_add_u32 s64, s74, 0x2000000
	s_addc_u32 s65, s75, 0
	s_add_u32 s2, s74, 0x4b00000
	s_addc_u32 s3, s75, 0
	v_readlane_b32 s36, v253, 5
	v_writelane_b32 v252, s2, 0
	v_readlane_b32 s44, v253, 13
	v_readlane_b32 s45, v253, 14
	v_writelane_b32 v252, s3, 1
	s_add_u32 s2, s74, 0x5300000
	s_addc_u32 s3, s75, 0
	v_writelane_b32 v252, s2, 2
	s_add_u32 s82, s74, 0x1a00000
	s_addc_u32 s83, s75, 0
	v_writelane_b32 v252, s3, 3
	v_readlane_b32 s2, v253, 60
	s_ashr_i32 s3, s96, 31
	s_ashr_i32 s2, s2, 31
	v_writelane_b32 v252, s2, 4
	s_add_u32 s2, s44, 0x200
	s_mov_b64 s[84:85], 0x80
	v_readlane_b32 s47, v253, 16
	v_writelane_b32 v252, s2, 5
	s_addc_u32 s2, s45, 0
	s_and_b32 s15, s1, 3
	s_add_i32 m0, s79, 0x18000
	v_lshl_add_u64 v[6:7], v[6:7], 0, s[84:85]
	s_mov_b32 s47, s3
	v_writelane_b32 v252, s2, 6
	s_lshl_b32 s7, s0, 6
	s_lshl_b32 s2, s0, 13
	s_lshl_b32 s3, s15, 12
	global_load_lds_dwordx4 v[6:7], off
	v_lshl_add_u64 v[4:5], v[4:5], 0, s[84:85]
	s_add_i32 m0, s79, 0x1a000
	s_add_i32 s97, s79, 0x8000
	s_add_i32 s78, s79, 0xa000
	global_load_lds_dwordx4 v[4:5], off
	v_lshl_add_u64 v[2:3], v[2:3], 0, s[84:85]
	s_mov_b32 m0, s97
	s_add_u32 s0, s34, 0x40080
	global_load_lds_dwordx4 v[2:3], off
	v_lshl_add_u64 v[0:1], v[0:1], 0, s[84:85]
	s_mov_b32 m0, s78
	s_addc_u32 s1, s35, 0
	global_load_lds_dwordx4 v[0:1], off
	s_add_i32 m0, s79, 0x1c000
	v_lshl_add_u64 v[0:1], s[0:1], 0, v[138:139]
	global_load_lds_dwordx4 v[0:1], off
	v_lshl_add_u64 v[0:1], s[0:1], 0, v[142:143]
	s_add_i32 m0, s79, 0x1e000
	v_lshlrev_b32_e32 v2, 6, v215
	global_load_lds_dwordx4 v[0:1], off
	s_waitcnt vmcnt(8)
	s_barrier
	v_bfe_u32 v1, v215, 4, 2
	v_lshlrev_b32_e32 v0, 4, v1
	s_movk_i32 s0, 0x3c0
	v_and_or_b32 v5, v2, s0, v0
	v_cmp_gt_u32_e64 s[0:1], 2, v1
	v_and_b32_e32 v2, 16, v215
	v_lshlrev_b32_e32 v144, 5, v1
	v_writelane_b32 v252, s0, 7
	v_lshlrev_b32_e32 v4, 3, v1
	v_cmp_eq_u32_e32 vcc, 0, v2
	v_writelane_b32 v252, s1, 8
	v_cmp_ne_u32_e64 s[4:5], 0, v1
	v_lshl_add_u64 v[2:3], s[72:73], 0, v[144:145]
	s_mov_b64 s[0:1], 0x2400000
	v_mov_b32_e32 v1, v145
	v_lshl_add_u64 v[148:149], v[2:3], 0, s[0:1]
	v_lshl_add_u64 v[2:3], s[74:75], 0, v[0:1]
	s_mov_b64 s[0:1], 0x1f00000
	s_cmpk_lt_u32 s33, 0x100
	v_lshl_add_u64 v[150:151], v[2:3], 0, s[0:1]
	s_cselect_b64 s[0:1], -1, 0
	v_lshlrev_b32_e32 v1, 8, v215
	v_writelane_b32 v252, s0, 9
	s_cmp_eq_u32 s15, 0
	v_and_b32_e32 v1, 0x38000, v1
	v_lshlrev_b32_e32 v2, 11, v10
	v_and_b32_e32 v153, 15, v215
	v_writelane_b32 v252, s1, 10
	s_cselect_b64 s[0:1], -1, 0
	v_or3_b32 v1, v8, v1, v2
	v_and_b32_e32 v6, 32, v68
	v_lshl_or_b32 v0, v153, 6, v0
	v_writelane_b32 v252, s0, 11
	v_add_u32_e32 v154, v1, v9
	v_lshlrev_b32_e32 v1, 4, v11
	v_bitop3_b32 v0, v0, s2, v6 bitop3:0xde
	s_waitcnt vmcnt(6)
	v_writelane_b32 v252, s1, 12
	v_and_b32_e32 v1, 0x78000, v1
	v_readlane_b32 s46, v253, 15
	v_readlane_b32 s48, v253, 17
	v_readlane_b32 s50, v253, 19
	v_readlane_b32 s51, v253, 20
	v_cndmask_b32_e64 v146, 1.0, -1.0, vcc
	v_or_b32_e32 v170, s7, v153
	v_bitop3_b32 v171, s3, v5, v6 bitop3:0xf6
	v_writelane_b32 v252, s7, 13
	v_or3_b32 v1, v8, v1, v2
	s_add_i32 s52, 0, 0x10000
	s_add_i32 s53, 0, 0x14000
	v_add_u32_e32 v181, 0, v0
	v_mbcnt_lo_u32_b32 v0, -1, 0
	s_mov_b32 s50, s96
	v_lshl_or_b32 v152, s15, 5, v4
	s_add_i32 s51, s7, 0x80
	v_or_b32_e32 v172, 16, v170
	v_or_b32_e32 v173, 32, v170
	v_or_b32_e32 v174, 48, v170
	v_add_u32_e32 v175, 0x80, v170
	s_movk_i32 s18, 0x90
	v_add_u32_e32 v176, 0x90, v170
	v_add_u32_e32 v177, 0xa0, v170
	v_add_u32_e32 v178, 0xb0, v170
	v_mov_b32_e32 v147, v146
	v_mov_b32_e32 v155, v145
	v_add_u32_e32 v156, v1, v9
	v_mov_b32_e32 v157, v145
	v_mov_b64_e32 v[158:159], 0xe0
	v_mov_b64_e32 v[160:161], 0xdf
	v_add_u32_e32 v179, s52, v171
	v_add_u32_e32 v180, s53, v171
	s_mov_b32 s90, 0x3e6d3388
	s_mov_b32 s92, 0x3f07dc22
	s_mov_b32 s48, 0xbf3a00e3
	s_mov_b32 s96, 0x3f35f0e3
	s_mov_b32 s12, 0xbe11a98e
	s_mov_b32 s14, 0x3e027906
	s_mov_b32 s66, 0xbf38aa3b
	s_movk_i32 s44, 0x1000
	s_movk_i32 s45, 0x300
	s_movk_i32 s33, 0x7fff
	v_mbcnt_hi_u32_b32 v182, -1, v0
	s_mov_b32 s36, 0
	s_mov_b32 s46, s6
	v_writelane_b32 v252, s16, 14
	v_readlane_b32 s37, v253, 6
	v_readlane_b32 s38, v253, 7
	v_readlane_b32 s39, v253, 8
	v_readlane_b32 s40, v253, 9
	v_readlane_b32 s41, v253, 10
	v_readlane_b32 s42, v253, 11
	v_readlane_b32 s43, v253, 12
	v_readlane_b32 s49, v253, 18
	s_barrier
	v_writelane_b32 v252, s17, 15
	s_branch .LBB0_349

.LBB0_695:
	s_and_b32 s1, s1, 3
	s_lshl_b32 s46, s2, 6
	s_lshl_b32 s8, s2, 13
	s_lshl_b32 s9, s1, 12
	s_add_u32 s20, s74, 0x7100000
	s_mov_b64 s[56:57], 0x80
	s_addc_u32 s21, s75, 0
	s_add_i32 m0, s16, 0x18000
	v_lshl_add_u64 v[6:7], v[6:7], 0, s[56:57]
	s_ashr_i32 s47, s39, 31
	global_load_lds_dwordx4 v[6:7], off
	v_lshl_add_u64 v[4:5], v[4:5], 0, s[56:57]
	s_add_i32 m0, s16, 0x1a000
	s_add_i32 s48, s16, 0x8000
	s_add_i32 s49, s16, 0xa000
	global_load_lds_dwordx4 v[4:5], off
	v_lshl_add_u64 v[0:1], v[0:1], 0, s[56:57]
	s_mov_b32 m0, s48
	s_add_u32 s2, s4, 0x10080
	global_load_lds_dwordx4 v[0:1], off
	v_lshl_add_u64 v[0:1], v[2:3], 0, s[56:57]
	s_mov_b32 m0, s49
	s_addc_u32 s3, s5, 0
	global_load_lds_dwordx4 v[0:1], off
	s_add_i32 m0, s16, 0x1c000
	v_lshl_add_u64 v[0:1], s[2:3], 0, v[130:131]
	global_load_lds_dwordx4 v[0:1], off
	v_lshl_add_u64 v[0:1], s[2:3], 0, v[134:135]
	s_add_i32 m0, s16, 0x1e000
	s_cmpk_lt_u32 s0, 0x100
	global_load_lds_dwordx4 v[0:1], off
	s_waitcnt vmcnt(8)
	s_barrier
	v_lshlrev_b32_e32 v0, 1, v8
	v_or_b32_e32 v1, v0, v159
	v_lshlrev_b32_e32 v3, 2, v200
	v_bitop3_b32 v164, s9, v1, v158 bitop3:0xf6
	v_mov_b32_e32 v1, v131
	s_cselect_b64 s[58:59], -1, 0
	s_cmp_gt_u32 s1, 1
	v_lshl_or_b32 v2, v200, 6, v0
	v_and_b32_e32 v3, 32, v3
	v_lshl_add_u64 v[0:1], s[74:75], 0, v[0:1]
	s_waitcnt vmcnt(6)
	s_cselect_b64 s[60:61], -1, 0
	s_lshl_b32 s14, s1, 6
	v_bitop3_b32 v2, v2, s8, v3 bitop3:0xde
	v_lshl_or_b32 v3, s1, 5, v8
	v_lshl_add_u64 v[0:1], v[0:1], 0, s[14:15]
	s_mov_b64 s[0:1], 0x6700000
	s_add_i32 s14, 0, 0x10000
	s_add_i32 s52, 0, 0x14000
	v_or_b32_e32 v166, 0x80, v200
	s_mov_b32 s50, 0xa000
	s_mov_b32 s51, 0x1e000
	v_subrev_u32_e32 v136, 64, v3
	v_mov_b32_e32 v137, v131
	v_lshl_add_u64 v[138:139], v[0:1], 0, s[0:1]
	v_mov_b64_e32 v[140:141], 0xa0
	v_mov_b64_e32 v[142:143], 0x9f
	v_add_u32_e32 v167, s14, v164
	v_add_u32_e32 v168, s52, v164
	v_add_u32_e32 v169, 0, v2
	s_movk_i32 s53, 0x90
	v_mov_b32_e32 v170, 0x358637bd
	s_movk_i32 s54, 0x5000
	s_movk_i32 s55, 0x7fff
	s_mov_b32 s78, 0x19000
	s_mov_b32 s79, 1.0
	v_mov_b32_e32 v171, 0x2800
	s_barrier
	s_branch .LBB0_698

.LBB0_824:
	s_lshl_b32 s4, s4, 5
	s_and_b32 s45, s4, 0x60
	s_lshl_b32 s44, s5, 6
	s_lshl_b32 s8, s5, 13
	s_lshl_b32 s9, s45, 7
	s_add_u32 s16, s74, 0x5b00000
	s_mov_b64 s[20:21], 0x80
	s_addc_u32 s17, s75, 0
	s_add_i32 m0, s39, 0x18000
	v_lshl_add_u64 v[6:7], v[6:7], 0, s[20:21]
	global_load_lds_dwordx4 v[6:7], off
	v_lshl_add_u64 v[4:5], v[4:5], 0, s[20:21]
	s_add_i32 m0, s39, 0x1a000
	s_add_i32 s46, s39, 0x8000
	s_add_i32 s47, s39, 0xa000
	global_load_lds_dwordx4 v[4:5], off
	v_lshl_add_u64 v[0:1], v[0:1], 0, s[20:21]
	s_mov_b32 m0, s46
	s_add_u32 s4, s6, 0x18080
	global_load_lds_dwordx4 v[0:1], off
	v_lshl_add_u64 v[0:1], v[2:3], 0, s[20:21]
	s_mov_b32 m0, s47
	s_addc_u32 s5, s7, 0
	global_load_lds_dwordx4 v[0:1], off
	s_add_i32 m0, s39, 0x1c000
	v_lshl_add_u64 v[0:1], s[4:5], 0, v[166:167]
	global_load_lds_dwordx4 v[0:1], off
	v_lshl_add_u64 v[0:1], s[4:5], 0, v[170:171]
	s_add_i32 m0, s39, 0x1e000
	v_lshlrev_b32_e32 v3, 2, v200
	global_load_lds_dwordx4 v[0:1], off
	s_waitcnt vmcnt(8)
	s_barrier
	v_bfe_u32 v1, v215, 4, 2
	v_lshlrev_b32_e32 v0, 4, v1
	v_or_b32_e32 v2, v0, v159
	v_lshl_or_b32 v0, v200, 6, v0
	v_and_b32_e32 v3, 32, v3
	v_bitop3_b32 v3, v0, s8, v3 bitop3:0xde
	v_lshlrev_b32_e32 v0, 3, v1
	v_cmp_gt_u32_e64 s[10:11], 2, v1
	v_and_b32_e32 v1, 16, v215
	v_cmp_eq_u32_e32 vcc, 0, v1
	s_waitcnt vmcnt(6)
	s_cmpk_lt_u32 s0, 0x100
	v_add_u16_e32 v1, v156, v157
	v_bitop3_b32 v201, s9, v2, v158 bitop3:0xf6
	v_cndmask_b32_e64 v174, 1.0, -1.0, vcc
	s_cselect_b64 s[56:57], -1, 0
	v_lshrrev_b16_e32 v1, 1, v1
	s_add_i32 s48, 0, 0x10000
	s_add_i32 s49, 0, 0x14000
	v_lshlrev_b32_e32 v172, 1, v0
	v_mbcnt_lo_u32_b32 v0, -1, 0
	s_sext_i32_i8 s55, s1
	v_or_b32_e32 v202, 16, v200
	v_or_b32_e32 v203, 32, v200
	v_or_b32_e32 v204, 48, v200
	v_mov_b32_e32 v175, v174
	v_add_lshl_u32 v176, v8, v1, 1
	v_mov_b32_e32 v177, v173
	v_add_lshl_u32 v178, v9, v1, 1
	v_mov_b32_e32 v179, v173
	v_mov_b64_e32 v[180:181], 0x60
	v_mov_b64_e32 v[182:183], 0x5f
	v_add_u32_e32 v205, s48, v201
	v_add_u32_e32 v206, s49, v201
	v_add_u32_e32 v207, 0, v3
	s_movk_i32 s50, 0x90
	v_mov_b32_e32 v208, 0x358637bd
	s_movk_i32 s51, 0x600
	v_mbcnt_hi_u32_b32 v209, -1, v0
	s_barrier
	s_branch .LBB0_827

.LBB0_1033:
	s_lshl_b32 s4, s4, 5
	s_mov_b64 s[8:9], 0x80
	s_and_b32 s4, s4, 0x60
	s_add_i32 m0, s31, 0x18000
	v_lshl_add_u64 v[8:9], v[8:9], 0, s[8:9]
	s_lshl_b32 s12, s1, 13
	s_lshl_b32 s13, s4, 7
	global_load_lds_dwordx4 v[8:9], off
	v_lshl_add_u64 v[6:7], v[6:7], 0, s[8:9]
	s_add_i32 m0, s31, 0x1a000
	s_add_i32 s48, s31, 0x8000
	s_add_i32 s49, s31, 0xa000
	global_load_lds_dwordx4 v[6:7], off
	v_lshl_add_u64 v[2:3], v[2:3], 0, s[8:9]
	s_mov_b32 m0, s48
	s_add_u32 s10, s34, 0x40080
	global_load_lds_dwordx4 v[2:3], off
	v_lshl_add_u64 v[2:3], v[4:5], 0, s[8:9]
	s_mov_b32 m0, s49
	s_addc_u32 s11, s35, 0
	global_load_lds_dwordx4 v[2:3], off
	s_add_i32 m0, s31, 0x1c000
	v_lshl_add_u64 v[2:3], s[10:11], 0, v[130:131]
	global_load_lds_dwordx4 v[2:3], off
	v_lshl_add_u64 v[2:3], s[10:11], 0, v[134:135]
	s_add_i32 m0, s31, 0x1e000
	v_lshlrev_b32_e32 v4, 6, v215
	global_load_lds_dwordx4 v[2:3], off
	s_waitcnt vmcnt(8)
	s_barrier
	v_and_b32_e32 v2, 15, v215
	v_lshlrev_b32_e32 v3, 1, v0
	s_movk_i32 s10, 0x3c0
	v_lshlrev_b32_e32 v5, 2, v215
	v_and_or_b32 v4, v4, s10, v3
	v_and_b32_e32 v5, 32, v5
	v_lshl_or_b32 v142, s1, 6, v2
	v_lshl_or_b32 v2, v2, 6, v3
	v_lshlrev_b32_e32 v3, 8, v215
	v_bitop3_b32 v143, s13, v4, v5 bitop3:0xf6
	v_and_b32_e32 v3, 0x38000, v3
	v_lshlrev_b32_e32 v4, 11, v11
	v_or3_b32 v3, v1, v3, v4
	v_add_u32_e32 v138, v3, v10
	v_lshlrev_b32_e32 v3, 4, v12
	s_waitcnt vmcnt(6)
	s_cmpk_lt_u32 s0, 0x100
	v_and_b32_e32 v3, 0x78000, v3
	v_bitop3_b32 v2, v2, s12, v5 bitop3:0xde
	s_cselect_b64 s[10:11], -1, 0
	v_or3_b32 v1, v1, v3, v4
	s_add_i32 s50, 0, 0x10000
	s_add_i32 s51, 0, 0x14000
	v_or_b32_e32 v144, 16, v142
	v_or_b32_e32 v145, 32, v142
	v_or_b32_e32 v146, 48, v142
	v_add_u32_e32 v147, 0x80, v142
	v_add_u32_e32 v148, 0x90, v142
	v_add_u32_e32 v149, 0xa0, v142
	v_add_u32_e32 v150, 0xb0, v142
	v_mov_b32_e32 v139, v137
	v_add_u32_e32 v140, v1, v10
	v_mov_b32_e32 v141, v137
	v_add_u32_e32 v151, s50, v143
	v_add_u32_e32 v152, s51, v143
	v_add_u32_e32 v153, 0, v2
	s_brev_b32 s52, 48
	s_lshl_b32 s4, s4, 1
	v_lshlrev_b32_e32 v136, 1, v0
	s_mov_b32 s53, s5
	s_barrier
	s_branch .LBB0_1036

.LBB0_1178:
	s_add_u32 s36, s74, 0xc000000
	v_readlane_b32 s16, v253, 21
	s_addc_u32 s37, s75, 0
	v_readlane_b32 s30, v253, 35
	v_readlane_b32 s31, v253, 36
	s_add_u32 s38, s74, 0x8000000
	v_readlane_b32 s12, v253, 62
	v_readlane_b32 s28, v253, 33
	v_readlane_b32 s29, v253, 34
	s_mov_b64 s[62:63], s[30:31]
	s_addc_u32 s39, s75, 0
	s_ashr_i32 s51, s12, 31
	s_ashr_i32 s65, s93, 31
	s_mov_b64 s[60:61], s[28:29]
	s_add_u32 s14, s60, 0x2c00
	s_addc_u32 s15, s61, 0
	v_readlane_b32 s17, v253, 22
	s_add_u32 s16, s60, 0x5800
	s_addc_u32 s17, s61, 0
	s_add_u32 s28, s60, 0x8400
	s_addc_u32 s29, s61, 0
	s_add_u32 s30, s60, 0xb000
	s_addc_u32 s31, s61, 0
	s_add_u32 s40, s60, 0xdc00
	s_addc_u32 s41, s61, 0
	s_add_u32 s44, s62, 0x2c00
	s_addc_u32 s45, s63, 0
	s_lshl_b32 s0, s0, 5
	s_mov_b64 s[52:53], 0x80
	s_and_b32 s56, s0, 0x60
	s_add_i32 m0, s46, 0x18000
	v_lshl_add_u64 v[6:7], v[6:7], 0, s[52:53]
	s_lshl_b32 s67, s1, 6
	s_lshl_b32 s11, s1, 13
	s_lshl_b32 s54, s56, 7
	global_load_lds_dwordx4 v[6:7], off
	v_lshl_add_u64 v[4:5], v[4:5], 0, s[52:53]
	s_add_i32 m0, s46, 0x1a000
	s_add_i32 s78, s46, 0x8000
	s_add_i32 s79, s46, 0xa000
	global_load_lds_dwordx4 v[4:5], off
	v_lshl_add_u64 v[0:1], v[0:1], 0, s[52:53]
	s_mov_b32 m0, s78
	s_add_u32 s0, s34, 0x40080
	global_load_lds_dwordx4 v[0:1], off
	v_lshl_add_u64 v[0:1], v[2:3], 0, s[52:53]
	s_mov_b32 m0, s79
	s_addc_u32 s1, s35, 0
	global_load_lds_dwordx4 v[0:1], off
	s_add_i32 m0, s46, 0x1c000
	v_lshl_add_u64 v[0:1], s[0:1], 0, v[162:163]
	global_load_lds_dwordx4 v[0:1], off
	v_lshl_add_u64 v[0:1], s[0:1], 0, v[166:167]
	s_add_i32 m0, s46, 0x1e000
	s_movk_i32 s0, 0x3c0
	global_load_lds_dwordx4 v[0:1], off
	s_waitcnt vmcnt(8)
	s_barrier
	v_lshlrev_b32_e32 v0, 1, v11
	v_lshlrev_b32_e32 v1, 6, v215
	v_and_b32_e32 v217, 15, v215
	v_and_or_b32 v1, v1, s0, v0
	v_and_b32_e32 v2, 32, v216
	v_lshl_or_b32 v0, v217, 6, v0
	v_bitop3_b32 v219, s54, v1, v2 bitop3:0xf6
	v_lshlrev_b32_e32 v1, 8, v215
	v_bitop3_b32 v0, v0, s11, v2 bitop3:0xde
	v_and_b32_e32 v1, 0x38000, v1
	v_lshlrev_b32_e32 v2, 11, v10
	v_or3_b32 v1, v8, v1, v2
	v_add_u32_e32 v168, v1, v9
	v_lshlrev_b32_e32 v1, 4, v12
	s_waitcnt vmcnt(6)
	s_cmpk_lt_u32 s10, 0x100
	v_and_b32_e32 v1, 0x78000, v1
	s_cselect_b64 s[54:55], -1, 0
	v_or3_b32 v1, v8, v1, v2
	s_add_i32 s81, 0, 0x10000
	s_add_i32 s82, 0, 0x14000
	v_cmp_eq_u32_e64 s[0:1], 15, v217
	v_cmp_eq_u32_e64 s[4:5], 0, v217
	v_cmp_gt_u32_e64 s[6:7], 2, v217
	v_cmp_lt_u32_e64 s[8:9], 13, v217
	v_add_u32_e32 v218, -12, v217
	s_mov_b32 s80, s12
	v_or_b32_e32 v220, s56, v11
	v_mov_b32_e32 v169, v163
	v_add_u32_e32 v170, v1, v9
	v_mov_b32_e32 v171, v163
	v_mov_b64_e32 v[172:173], 0x2c0
	v_mov_b64_e32 v[174:175], 0x2bf
	v_add_u32_e32 v221, s81, v219
	v_add_u32_e32 v222, s82, v219
	v_add_u32_e32 v223, 0, v0
	s_movk_i32 s83, 0x5800
	s_movk_i32 s84, 0x1600
	v_readlane_b32 s13, v253, 63
	v_readlane_b32 s18, v253, 23
	v_readlane_b32 s19, v253, 24
	v_readlane_b32 s20, v253, 25
	v_readlane_b32 s21, v253, 26
	v_readlane_b32 s22, v253, 27
	v_readlane_b32 s23, v253, 28
	v_readlane_b32 s24, v253, 29
	v_readlane_b32 s25, v253, 30
	v_readlane_b32 s26, v253, 31
	v_readlane_b32 s27, v253, 32
	s_barrier
	s_branch .LBB0_1181

.LBB0_1423:
	s_lshl_b32 s4, s4, 5
	s_mov_b64 s[8:9], 0x80
	s_and_b32 s4, s4, 0x60
	s_add_i32 m0, s31, 0x18000
	v_lshl_add_u64 v[8:9], v[8:9], 0, s[8:9]
	s_lshl_b32 s12, s1, 13
	s_lshl_b32 s13, s4, 7
	global_load_lds_dwordx4 v[8:9], off
	v_lshl_add_u64 v[6:7], v[6:7], 0, s[8:9]
	s_add_i32 m0, s31, 0x1a000
	s_add_i32 s36, s31, 0x8000
	s_add_i32 s37, s31, 0xa000
	global_load_lds_dwordx4 v[6:7], off
	v_lshl_add_u64 v[2:3], v[2:3], 0, s[8:9]
	s_mov_b32 m0, s36
	s_add_u32 s10, s20, 0xb0080
	global_load_lds_dwordx4 v[2:3], off
	v_lshl_add_u64 v[2:3], v[4:5], 0, s[8:9]
	s_mov_b32 m0, s37
	s_addc_u32 s11, s21, 0
	global_load_lds_dwordx4 v[2:3], off
	s_add_i32 m0, s31, 0x1c000
	v_lshl_add_u64 v[2:3], s[10:11], 0, v[130:131]
	global_load_lds_dwordx4 v[2:3], off
	v_lshl_add_u64 v[2:3], s[10:11], 0, v[134:135]
	s_add_i32 m0, s31, 0x1e000
	v_lshlrev_b32_e32 v4, 6, v215
	global_load_lds_dwordx4 v[2:3], off
	s_waitcnt vmcnt(8)
	s_barrier
	v_and_b32_e32 v2, 15, v215
	v_lshlrev_b32_e32 v3, 1, v0
	s_movk_i32 s10, 0x3c0
	v_lshlrev_b32_e32 v5, 2, v215
	v_and_or_b32 v4, v4, s10, v3
	v_and_b32_e32 v5, 32, v5
	v_lshl_or_b32 v142, s1, 6, v2
	v_lshl_or_b32 v2, v2, 6, v3
	s_waitcnt vmcnt(6)
	s_cmpk_lt_u32 s0, 0x100
	v_add_u16_e32 v1, v1, v10
	v_bitop3_b32 v2, v2, s12, v5 bitop3:0xde
	v_bitop3_b32 v143, s13, v4, v5 bitop3:0xf6
	s_cselect_b64 s[10:11], -1, 0
	v_lshrrev_b16_e32 v1, 1, v1
	s_add_i32 s38, 0, 0x10000
	s_add_i32 s39, 0, 0x14000
	v_or_b32_e32 v144, 16, v142
	v_or_b32_e32 v145, 32, v142
	v_or_b32_e32 v146, 48, v142
	v_add_u32_e32 v147, 0x80, v142
	v_add_u32_e32 v148, 0x90, v142
	v_add_u32_e32 v149, 0xa0, v142
	v_add_u32_e32 v150, 0xb0, v142
	v_add_lshl_u32 v138, v11, v1, 1
	v_mov_b32_e32 v139, v137
	v_add_lshl_u32 v140, v12, v1, 1
	v_mov_b32_e32 v141, v137
	v_add_u32_e32 v151, s38, v143
	v_add_u32_e32 v152, s39, v143
	v_add_u32_e32 v153, 0, v2
	s_brev_b32 s40, 32
	s_lshl_b32 s4, s4, 1
	v_lshlrev_b32_e32 v136, 1, v0
	s_mov_b32 s41, s5
	s_barrier
	s_branch .LBB0_1426
